# w_in GEMM: next tile's SA(1,1) LDS-DMA pair issued before the epilogue stores, first counted wait of the next tile relaxed to vmcnt(22)
# speedup vs baseline: 1.0420x; 1.0024x over previous
; #define PG8_STAGE(bufoff, gbase, voff) do { _Pragma("unroll") for (int _i = 0; _i < 2; ++_i) \
;         __builtin_amdgcn_global_load_lds((const unsigned*)((const char*)(gbase) + (voff)[_i]), (LAS unsigned*)(lds + (bufoff) + ldsw + _i * 8192), 16, 0, 0); } while (0)
; #define PG8_WAIT_V(n) asm volatile("s_waitcnt vmcnt(" #n ")" ::: "memory")
; #define PG8_BAR __builtin_amdgcn_s_barrier()
; template <class Epi, class Sched>
; __device__ __forceinline__ void gemm_phase(LAS unsigned char* lds, const Gemm g, const Sched& S, const Epi& E) {
;     ...
;     const char* cA = (const char*)g.A + (size_t)cur.z * g.zA + (size_t)cur.pm * tstep; const char* cB = (const char*)g.Bt + (size_t)cur.z * g.zB + (size_t)cur.pn * tstep;
;     PG8_STAGE(PG8_SB(0, 0), cB, voffB); PG8_STAGE(PG8_SA(0, 0), cA, voffA); PG8_STAGE(PG8_SB(0, 1), cB + hstep, voffB); PG8_STAGE(PG8_SA(0, 1), cA + hstep, voffA);
;     if (wr == 1) PG8_BAR;
;     PG8_WAIT_V(4); PG8_BAR;
;     PG8_STAGE(PG8_SB(1, 0), cB + kstep, voffB); PG8_STAGE(PG8_SA(1, 0), cA + kstep, voffA); PG8_STAGE(PG8_SB(1, 1), cB + hstep + kstep, voffB);
;     PG8_WAIT_V(6); PG8_BAR;
.LBB0_848:
	s_add_u32 s0, s14, 0x9c00000
	s_addc_u32 s1, s15, 0
	s_lshl_b32 s8, s8, 5
	s_and_b32 s11, s8, 0x60
	s_add_i32 m0, s7, 0x18000
	v_lshl_add_u64 v[6:7], v[6:7], 0, s[82:83]
	s_lshl_b32 s10, s5, 13
	s_lshl_b32 s12, s11, 7
	s_waitcnt vmcnt(4)
	s_barrier
	global_load_lds_dwordx4 v[6:7], off
	v_lshl_add_u64 v[4:5], v[4:5], 0, s[82:83]
	s_add_i32 m0, s7, 0x1a000
	s_add_i32 s28, s7, 0x8000
	s_add_i32 s29, s7, 0xa000
	global_load_lds_dwordx4 v[4:5], off
	v_lshl_add_u64 v[2:3], v[2:3], 0, s[82:83]
	s_mov_b32 m0, s28
	s_add_u32 s8, s16, 0x80080
	global_load_lds_dwordx4 v[2:3], off
	v_lshl_add_u64 v[0:1], v[0:1], 0, s[82:83]
	s_mov_b32 m0, s29
	s_addc_u32 s9, s17, 0
	global_load_lds_dwordx4 v[0:1], off
	s_add_i32 m0, s7, 0x1c000
	v_lshl_add_u64 v[0:1], s[8:9], 0, v[176:177]
	global_load_lds_dwordx4 v[0:1], off
	v_lshl_add_u64 v[0:1], s[8:9], 0, v[128:129]
	s_add_i32 m0, s7, 0x1e000
	s_sext_i32_i16 s33, s4
	global_load_lds_dwordx4 v[0:1], off
	v_lshrrev_b32_e32 v1, 1, v8
	v_and_b32_e32 v1, 24, v1
	v_and_b32_e32 v0, 15, v8
	v_lshlrev_b32_e32 v2, 1, v1
	v_lshl_or_b32 v138, s5, 6, v0
	v_lshl_or_b32 v0, v0, 6, v2
	v_lshlrev_b32_e32 v2, 2, v8
	v_and_b32_e32 v2, 32, v2
	v_bitop3_b32 v3, v0, s10, v2 bitop3:0xde
	v_bitop3_b32 v139, v0, s12, v2 bitop3:0xde
	v_lshlrev_b32_e32 v0, 15, v9
	v_and_b32_e32 v0, 0xffff0000, v0
	v_or_b32_e32 v140, s11, v1
	v_lshl_add_u32 v0, v10, 12, v0
	v_and_b32_e32 v1, 1, v9
	v_lshl_or_b32 v0, v1, 6, v0
	v_lshl_add_u32 v134, v11, 1, v0
	v_lshlrev_b32_e32 v0, 15, v13
	v_and_b32_e32 v0, 0xffff0000, v0
	s_waitcnt vmcnt(6)
	v_lshl_add_u32 v0, v12, 12, v0
	v_and_b32_e32 v1, 1, v13
	v_lshl_or_b32 v0, v1, 6, v0
	s_ashr_i32 s30, s68, 31
	v_mov_b32_e32 v135, v177
	v_lshl_add_u32 v136, v14, 1, v0
	v_mov_b32_e32 v137, v177
	s_mov_b32 s31, 0
	v_add_u32_e32 v141, 0, v3
	s_barrier
	s_mov_b32 s100, 0

; #define PG8_STAGE(bufoff, gbase, voff) do { _Pragma("unroll") for (int _i = 0; _i < 2; ++_i) \
;         __builtin_amdgcn_global_load_lds((const unsigned*)((const char*)(gbase) + (voff)[_i]), (LAS unsigned*)(lds + (bufoff) + ldsw + _i * 8192), 16, 0, 0); } while (0)
; #define PG8_LDA(dst, b, h) do { _Pragma("unroll") for (int m = 0; m < 4; ++m) _Pragma("unroll") for (int k = 0; k < 2; ++k) dst[m][k] = *(const LAS bf16x8*)(lds + PG8_SA(b, h) + aoff + m * 2048 + k * 1024); } while (0)
; #define PG8_LDB(dst, b, h) do { _Pragma("unroll") for (int n = 0; n < 2; ++n) _Pragma("unroll") for (int k = 0; k < 2; ++k) dst[n][k] = *(const LAS bf16x8*)(lds + PG8_SB(b, h) + boff + n * 2048 + k * 1024); } while (0)
; #define PG8_MMA(ai, bj, At, Bt) do { __builtin_amdgcn_s_setprio(1); _Pragma("unroll") for (int m = 0; m < 4; ++m) _Pragma("unroll") for (int n = 0; n < 2; ++n) _Pragma("unroll") for (int k = 0; k < 2; ++k) \
;         acc[ai][bj][m][n] = __builtin_amdgcn_mfma_f32_16x16x32_bf16(Bt[n][k], At[m][k], acc[ai][bj][m][n], 0, 0, 0); __builtin_amdgcn_s_setprio(0); } while (0)
; #define PG8_WAIT_V(n) asm volatile("s_waitcnt vmcnt(" #n ")" ::: "memory")
; #define PG8_WAIT_L(n) asm volatile("s_waitcnt lgkmcnt(" #n ")" ::: "memory")
; #define PG8_BAR __builtin_amdgcn_s_barrier()
; #define PG8_SCHED __builtin_amdgcn_sched_barrier(0)
; template <class Epi, class Sched>
; __device__ __forceinline__ void gemm_phase(LAS unsigned char* lds, const Gemm g, const Sched& S, const Epi& E) {
;     ...
;             PG8_LDB(B0, 0, 0); PG8_SCHED; PG8_LDA(At, 0, 0); PG8_STAGE(PG8_SA(1, 1), a1 + hstep, voffA);
;             PG8_WAIT_L(8); PG8_BAR; PG8_WAIT_L(0); PG8_MMA(0, 0, At, B0); PG8_BAR; PG8_SCHED;
;             PG8_LDB(B1, 0, 1); PG8_STAGE(PG8_SB(0, 0), b2, voffB);
;             PG8_BAR; PG8_WAIT_L(0); PG8_MMA(0, 1, At, B1); PG8_BAR;
;             PG8_LDA(At, 0, 1); PG8_STAGE(PG8_SA(0, 0), a2, voffA);
;             PG8_BAR; PG8_WAIT_L(0); PG8_MMA(1, 0, At, B0); PG8_BAR; PG8_SCHED;
;             PG8_STAGE(PG8_SB(0, 1), b2 + hstep, voffB);
;             PG8_WAIT_V(6); PG8_BAR; PG8_MMA(1, 1, At, B1); PG8_BAR;
.LBB0_852:
	s_add_u32 s18, s16, 0xfff80080
	s_addc_u32 s19, s17, -1
	s_add_i32 s39, 0, 0x10000
	v_add_u32_e32 v154, s39, v139
	ds_read_b128 v[142:145], v154
	ds_read_b128 v[146:149], v154 offset:1024
	ds_read_b128 v[150:153], v154 offset:2048
	ds_read_b128 v[154:157], v154 offset:3072
	s_cmp_eq_u32 s38, 28
	s_cselect_b32 s21, s11, s19
	s_cselect_b32 s20, s34, s18
	s_cselect_b32 s19, s9, s37
	s_cselect_b32 s18, s35, s36
	v_lshl_add_u64 v[174:175], s[16:17], 0, v[136:137]
	s_add_i32 m0, s7, 0xc000
	ds_read_b128 v[158:161], v141
	ds_read_b128 v[162:165], v141 offset:1024
	ds_read_b128 v[166:169], v141 offset:2048
	ds_read_b128 v[170:173], v141 offset:3072
	ds_read_b128 v[192:195], v141 offset:4096
	ds_read_b128 v[196:199], v141 offset:5120
	ds_read_b128 v[200:203], v141 offset:6144
	ds_read_b128 v[204:207], v141 offset:7168
	s_cmp_lg_u32 s100, 0
	s_cbranch_scc1 .Lgh_skip_win
	global_load_lds_dwordx4 v[174:175], off
	v_lshl_add_u64 v[174:175], s[16:17], 0, v[134:135]
	s_add_i32 m0, s7, 0xe000
	s_nop 0
	global_load_lds_dwordx4 v[174:175], off
.Lgh_skip_win:
	s_waitcnt lgkmcnt(8)
	s_barrier
	s_waitcnt lgkmcnt(0)
	s_setprio 1
	s_waitcnt lgkmcnt(0)
	v_mfma_f32_16x16x32_bf16 v[124:127], v[142:145], v[158:161], v[124:127]
	v_mfma_f32_16x16x32_bf16 v[120:123], v[150:153], v[158:161], v[120:123]
	v_mfma_f32_16x16x32_bf16 v[116:119], v[142:145], v[166:169], v[116:119]
	v_mfma_f32_16x16x32_bf16 v[112:115], v[150:153], v[166:169], v[112:115]
	v_mfma_f32_16x16x32_bf16 v[100:103], v[142:145], v[192:195], v[100:103]
	v_mfma_f32_16x16x32_bf16 v[96:99], v[150:153], v[192:195], v[96:99]
	v_mfma_f32_16x16x32_bf16 v[84:87], v[142:145], v[200:203], v[84:87]
	v_mfma_f32_16x16x32_bf16 v[80:83], v[150:153], v[200:203], v[80:83]
	v_mfma_f32_16x16x32_bf16 v[124:127], v[146:149], v[162:165], v[124:127]
	v_mfma_f32_16x16x32_bf16 v[120:123], v[154:157], v[162:165], v[120:123]
	v_mfma_f32_16x16x32_bf16 v[116:119], v[146:149], v[170:173], v[116:119]
	v_mfma_f32_16x16x32_bf16 v[112:115], v[154:157], v[170:173], v[112:115]
	v_mfma_f32_16x16x32_bf16 v[100:103], v[146:149], v[196:199], v[100:103]
	v_mfma_f32_16x16x32_bf16 v[96:99], v[154:157], v[196:199], v[96:99]
	v_mfma_f32_16x16x32_bf16 v[84:87], v[146:149], v[204:207], v[84:87]
	v_mfma_f32_16x16x32_bf16 v[80:83], v[154:157], v[204:207], v[80:83]
	s_setprio 0
	s_barrier
	s_add_i32 s42, 0, 0x14000
	v_add_u32_e32 v174, s42, v139
	s_add_i32 s39, s39, s23
	ds_read_b128 v[208:211], v174
	ds_read_b128 v[212:215], v174 offset:1024
	ds_read_b128 v[216:219], v174 offset:2048
	ds_read_b128 v[220:223], v174 offset:3072
	v_lshl_add_u64 v[174:175], s[18:19], 0, v[176:177]
	s_mov_b32 m0, s39
	v_lshl_add_u64 v[224:225], s[18:19], 0, v[128:129]
	global_load_lds_dwordx4 v[174:175], off
	s_add_i32 m0, s39, 0x2000
	s_nop 0
	global_load_lds_dwordx4 v[224:225], off
	s_barrier
	s_waitcnt lgkmcnt(0)
	s_setprio 1
	s_waitcnt lgkmcnt(0)
	v_mfma_f32_16x16x32_bf16 v[108:111], v[208:211], v[158:161], v[108:111]
	v_mfma_f32_16x16x32_bf16 v[104:107], v[216:219], v[158:161], v[104:107]
	v_mfma_f32_16x16x32_bf16 v[92:95], v[208:211], v[166:169], v[92:95]
	v_mfma_f32_16x16x32_bf16 v[88:91], v[216:219], v[166:169], v[88:91]
	v_mfma_f32_16x16x32_bf16 v[76:79], v[208:211], v[192:195], v[76:79]
	v_mfma_f32_16x16x32_bf16 v[72:75], v[216:219], v[192:195], v[72:75]
	v_mfma_f32_16x16x32_bf16 v[68:71], v[208:211], v[200:203], v[68:71]
	v_mfma_f32_16x16x32_bf16 v[64:67], v[216:219], v[200:203], v[64:67]
	v_mfma_f32_16x16x32_bf16 v[108:111], v[212:215], v[162:165], v[108:111]
	v_mfma_f32_16x16x32_bf16 v[104:107], v[220:223], v[162:165], v[104:107]
	v_mfma_f32_16x16x32_bf16 v[92:95], v[212:215], v[170:173], v[92:95]
	v_mfma_f32_16x16x32_bf16 v[88:91], v[220:223], v[170:173], v[88:91]
	v_mfma_f32_16x16x32_bf16 v[76:79], v[212:215], v[196:199], v[76:79]
	v_mfma_f32_16x16x32_bf16 v[72:75], v[220:223], v[196:199], v[72:75]
	v_mfma_f32_16x16x32_bf16 v[68:71], v[212:215], v[204:207], v[68:71]
	v_mfma_f32_16x16x32_bf16 v[64:67], v[220:223], v[204:207], v[64:67]
	s_setprio 0
	s_mov_b32 m0, s7
	v_lshl_add_u64 v[226:227], s[20:21], 0, v[132:133]
	s_barrier
	ds_read_b128 v[158:161], v141 offset:16384
	ds_read_b128 v[162:165], v141 offset:17408
	ds_read_b128 v[166:169], v141 offset:18432
	ds_read_b128 v[170:173], v141 offset:19456
	ds_read_b128 v[192:195], v141 offset:20480
	ds_read_b128 v[196:199], v141 offset:21504
	ds_read_b128 v[200:203], v141 offset:22528
	ds_read_b128 v[204:207], v141 offset:23552
	global_load_lds_dwordx4 v[226:227], off
	v_lshl_add_u64 v[228:229], s[20:21], 0, v[130:131]
	s_mov_b32 m0, s25
	s_nop 0
	global_load_lds_dwordx4 v[228:229], off
	s_barrier
	s_waitcnt lgkmcnt(0)
	s_setprio 1
	s_waitcnt lgkmcnt(0)
	v_mfma_f32_16x16x32_bf16 v[60:63], v[142:145], v[158:161], v[60:63]
	v_mfma_f32_16x16x32_bf16 v[56:59], v[150:153], v[158:161], v[56:59]
	v_mfma_f32_16x16x32_bf16 v[52:55], v[142:145], v[166:169], v[52:55]
	v_mfma_f32_16x16x32_bf16 v[48:51], v[150:153], v[166:169], v[48:51]
	v_mfma_f32_16x16x32_bf16 v[36:39], v[142:145], v[192:195], v[36:39]
	v_mfma_f32_16x16x32_bf16 v[32:35], v[150:153], v[192:195], v[32:35]
	v_mfma_f32_16x16x32_bf16 v[20:23], v[142:145], v[200:203], v[20:23]
	v_mfma_f32_16x16x32_bf16 v[16:19], v[150:153], v[200:203], v[16:19]
	v_mfma_f32_16x16x32_bf16 v[60:63], v[146:149], v[162:165], v[60:63]
	v_mfma_f32_16x16x32_bf16 v[56:59], v[154:157], v[162:165], v[56:59]
	v_mfma_f32_16x16x32_bf16 v[52:55], v[146:149], v[170:173], v[52:55]
	v_mfma_f32_16x16x32_bf16 v[48:51], v[154:157], v[170:173], v[48:51]
	v_mfma_f32_16x16x32_bf16 v[36:39], v[146:149], v[196:199], v[36:39]
	v_mfma_f32_16x16x32_bf16 v[32:35], v[154:157], v[196:199], v[32:35]
	v_mfma_f32_16x16x32_bf16 v[20:23], v[146:149], v[204:207], v[20:23]
	v_mfma_f32_16x16x32_bf16 v[16:19], v[154:157], v[204:207], v[16:19]
	s_setprio 0
	s_barrier
	s_add_u32 s40, s18, 0x80000
	s_addc_u32 s41, s19, 0
	s_add_i32 s39, s42, s23
	v_lshl_add_u64 v[142:143], s[40:41], 0, v[176:177]
	s_mov_b32 m0, s39
	s_nop 0
	global_load_lds_dwordx4 v[142:143], off
	v_lshl_add_u64 v[142:143], s[40:41], 0, v[128:129]
	s_add_i32 m0, s39, 0x2000
	s_nop 0
	global_load_lds_dwordx4 v[142:143], off
	s_cmp_lg_u32 s100, 0
	s_cbranch_scc1 .Lgh_relax_win
	s_waitcnt vmcnt(6)
; #define PG8_STAGE(bufoff, gbase, voff) do { _Pragma("unroll") for (int _i = 0; _i < 2; ++_i) \
;         __builtin_amdgcn_global_load_lds((const unsigned*)((const char*)(gbase) + (voff)[_i]), (LAS unsigned*)(lds + (bufoff) + ldsw + _i * 8192), 16, 0, 0); } while (0)
; #define PG8_LDA(dst, b, h) do { _Pragma("unroll") for (int m = 0; m < 4; ++m) _Pragma("unroll") for (int k = 0; k < 2; ++k) dst[m][k] = *(const LAS bf16x8*)(lds + PG8_SA(b, h) + aoff + m * 2048 + k * 1024); } while (0)
; #define PG8_LDB(dst, b, h) do { _Pragma("unroll") for (int n = 0; n < 2; ++n) _Pragma("unroll") for (int k = 0; k < 2; ++k) dst[n][k] = *(const LAS bf16x8*)(lds + PG8_SB(b, h) + boff + n * 2048 + k * 1024); } while (0)
; #define PG8_MMA(ai, bj, At, Bt) do { __builtin_amdgcn_s_setprio(1); _Pragma("unroll") for (int m = 0; m < 4; ++m) _Pragma("unroll") for (int n = 0; n < 2; ++n) _Pragma("unroll") for (int k = 0; k < 2; ++k) \
;         acc[ai][bj][m][n] = __builtin_amdgcn_mfma_f32_16x16x32_bf16(Bt[n][k], At[m][k], acc[ai][bj][m][n], 0, 0, 0); __builtin_amdgcn_s_setprio(0); } while (0)
; #define PG8_WAIT_V(n) asm volatile("s_waitcnt vmcnt(" #n ")" ::: "memory")
; #define PG8_WAIT_L(n) asm volatile("s_waitcnt lgkmcnt(" #n ")" ::: "memory")
; #define PG8_BAR __builtin_amdgcn_s_barrier()
; #define PG8_SCHED __builtin_amdgcn_sched_barrier(0)
; template <class Epi, class Sched>
; __device__ __forceinline__ void gemm_phase(LAS unsigned char* lds, const Gemm g, const Sched& S, const Epi& E) {
;     ...
;             PG8_WAIT_V(6); PG8_BAR; PG8_MMA(1, 1, At, B1); PG8_BAR;
;             PG8_LDB(B0, 1, 0); PG8_SCHED; PG8_LDA(At, 1, 0); PG8_STAGE(PG8_SA(0, 1), a2 + hstep, voffA);
;             PG8_WAIT_L(8); PG8_BAR; PG8_WAIT_L(0); PG8_MMA(0, 0, At, B0); PG8_BAR; PG8_SCHED;
;             PG8_LDB(B1, 1, 1); PG8_STAGE(PG8_SB(1, 0), b3, voffB);
;             PG8_BAR; PG8_WAIT_L(0); PG8_MMA(0, 1, At, B1); PG8_BAR;
;             PG8_LDA(At, 1, 1); PG8_STAGE(PG8_SA(1, 0), a3, voffA);
;             PG8_BAR; PG8_WAIT_L(0); PG8_MMA(1, 0, At, B0); PG8_BAR; PG8_SCHED;
.Lgh_back_win:
	s_barrier
	s_setprio 1
	v_mfma_f32_16x16x32_bf16 v[44:47], v[208:211], v[158:161], v[44:47]
	v_mfma_f32_16x16x32_bf16 v[40:43], v[216:219], v[158:161], v[40:43]
	v_mfma_f32_16x16x32_bf16 v[28:31], v[208:211], v[166:169], v[28:31]
	v_mfma_f32_16x16x32_bf16 v[24:27], v[216:219], v[166:169], v[24:27]
	v_mfma_f32_16x16x32_bf16 v[12:15], v[208:211], v[192:195], v[12:15]
	v_mfma_f32_16x16x32_bf16 v[8:11], v[216:219], v[192:195], v[8:11]
	v_mfma_f32_16x16x32_bf16 v[4:7], v[208:211], v[200:203], v[4:7]
	v_mfma_f32_16x16x32_bf16 v[0:3], v[216:219], v[200:203], v[0:3]
	v_mfma_f32_16x16x32_bf16 v[44:47], v[212:215], v[162:165], v[44:47]
	v_mfma_f32_16x16x32_bf16 v[40:43], v[220:223], v[162:165], v[40:43]
	v_mfma_f32_16x16x32_bf16 v[28:31], v[212:215], v[170:173], v[28:31]
	v_mfma_f32_16x16x32_bf16 v[24:27], v[220:223], v[170:173], v[24:27]
	v_mfma_f32_16x16x32_bf16 v[12:15], v[212:215], v[196:199], v[12:15]
	v_mfma_f32_16x16x32_bf16 v[8:11], v[220:223], v[196:199], v[8:11]
	v_mfma_f32_16x16x32_bf16 v[4:7], v[212:215], v[204:207], v[4:7]
	v_mfma_f32_16x16x32_bf16 v[0:3], v[220:223], v[204:207], v[0:3]
	s_setprio 0
	s_add_i32 s39, 0, 0x18000
	v_add_u32_e32 v154, s39, v139
	s_barrier
	ds_read_b128 v[142:145], v154
	ds_read_b128 v[146:149], v154 offset:1024
	ds_read_b128 v[150:153], v154 offset:2048
	ds_read_b128 v[154:157], v154 offset:3072
	s_add_u32 s20, s20, 0x80000
	s_addc_u32 s21, s21, 0
	s_mov_b32 m0, s26
	v_lshl_add_u64 v[208:209], s[20:21], 0, v[132:133]
	ds_read_b128 v[158:161], v141 offset:32768
	ds_read_b128 v[162:165], v141 offset:33792
	ds_read_b128 v[166:169], v141 offset:34816
	ds_read_b128 v[170:173], v141 offset:35840
	ds_read_b128 v[192:195], v141 offset:36864
	ds_read_b128 v[196:199], v141 offset:37888
	ds_read_b128 v[200:203], v141 offset:38912
	ds_read_b128 v[204:207], v141 offset:39936
	global_load_lds_dwordx4 v[208:209], off
	v_lshl_add_u64 v[208:209], s[20:21], 0, v[130:131]
	s_mov_b32 m0, s27
	s_nop 0
	global_load_lds_dwordx4 v[208:209], off
	s_waitcnt lgkmcnt(8)
	s_barrier
	s_waitcnt lgkmcnt(0)
	s_setprio 1
	s_waitcnt lgkmcnt(0)
	v_mfma_f32_16x16x32_bf16 v[124:127], v[142:145], v[158:161], v[124:127]
	v_mfma_f32_16x16x32_bf16 v[120:123], v[150:153], v[158:161], v[120:123]
	v_mfma_f32_16x16x32_bf16 v[116:119], v[142:145], v[166:169], v[116:119]
	v_mfma_f32_16x16x32_bf16 v[112:115], v[150:153], v[166:169], v[112:115]
	v_mfma_f32_16x16x32_bf16 v[100:103], v[142:145], v[192:195], v[100:103]
	v_mfma_f32_16x16x32_bf16 v[96:99], v[150:153], v[192:195], v[96:99]
	v_mfma_f32_16x16x32_bf16 v[84:87], v[142:145], v[200:203], v[84:87]
	v_mfma_f32_16x16x32_bf16 v[80:83], v[150:153], v[200:203], v[80:83]
	v_mfma_f32_16x16x32_bf16 v[124:127], v[146:149], v[162:165], v[124:127]
	v_mfma_f32_16x16x32_bf16 v[120:123], v[154:157], v[162:165], v[120:123]
	v_mfma_f32_16x16x32_bf16 v[116:119], v[146:149], v[170:173], v[116:119]
	v_mfma_f32_16x16x32_bf16 v[112:115], v[154:157], v[170:173], v[112:115]
	v_mfma_f32_16x16x32_bf16 v[100:103], v[146:149], v[196:199], v[100:103]
	v_mfma_f32_16x16x32_bf16 v[96:99], v[154:157], v[196:199], v[96:99]
	v_mfma_f32_16x16x32_bf16 v[84:87], v[146:149], v[204:207], v[84:87]
	v_mfma_f32_16x16x32_bf16 v[80:83], v[154:157], v[204:207], v[80:83]
	s_setprio 0
	s_barrier
	s_add_i32 s20, 0, 0x1c000
	s_add_i32 s21, s39, s23
	v_add_u32_e32 v191, s20, v139
	v_lshl_add_u64 v[174:175], v[174:175], 0, s[82:83]
	s_mov_b32 m0, s21
	ds_read_b128 v[208:211], v191
	ds_read_b128 v[212:215], v191 offset:1024
	ds_read_b128 v[216:219], v191 offset:2048
	ds_read_b128 v[220:223], v191 offset:3072
	global_load_lds_dwordx4 v[174:175], off
	v_lshl_add_u64 v[174:175], v[224:225], 0, s[82:83]
	s_add_i32 m0, s21, 0x2000
	s_nop 0
	global_load_lds_dwordx4 v[174:175], off
	s_barrier
	s_waitcnt lgkmcnt(0)
	s_setprio 1
	s_waitcnt lgkmcnt(0)
	v_mfma_f32_16x16x32_bf16 v[108:111], v[208:211], v[158:161], v[108:111]
	v_mfma_f32_16x16x32_bf16 v[104:107], v[216:219], v[158:161], v[104:107]
	v_mfma_f32_16x16x32_bf16 v[92:95], v[208:211], v[166:169], v[92:95]
	v_mfma_f32_16x16x32_bf16 v[88:91], v[216:219], v[166:169], v[88:91]
	v_mfma_f32_16x16x32_bf16 v[76:79], v[208:211], v[192:195], v[76:79]
	v_mfma_f32_16x16x32_bf16 v[72:75], v[216:219], v[192:195], v[72:75]
	v_mfma_f32_16x16x32_bf16 v[68:71], v[208:211], v[200:203], v[68:71]
	v_mfma_f32_16x16x32_bf16 v[64:67], v[216:219], v[200:203], v[64:67]
	v_mfma_f32_16x16x32_bf16 v[108:111], v[212:215], v[162:165], v[108:111]
	v_mfma_f32_16x16x32_bf16 v[104:107], v[220:223], v[162:165], v[104:107]
	v_mfma_f32_16x16x32_bf16 v[92:95], v[212:215], v[170:173], v[92:95]
	v_mfma_f32_16x16x32_bf16 v[88:91], v[220:223], v[170:173], v[88:91]
	v_mfma_f32_16x16x32_bf16 v[76:79], v[212:215], v[196:199], v[76:79]
	v_mfma_f32_16x16x32_bf16 v[72:75], v[220:223], v[196:199], v[72:75]
	v_mfma_f32_16x16x32_bf16 v[68:71], v[212:215], v[204:207], v[68:71]
	v_mfma_f32_16x16x32_bf16 v[64:67], v[220:223], v[204:207], v[64:67]
	s_setprio 0
	s_mov_b32 m0, s28
	v_lshl_add_u64 v[174:175], v[226:227], 0, s[82:83]
	s_barrier
	ds_read_b128 v[158:161], v141 offset:49152
	ds_read_b128 v[162:165], v141 offset:50176
	ds_read_b128 v[166:169], v141 offset:51200
	ds_read_b128 v[170:173], v141 offset:52224
	ds_read_b128 v[192:195], v141 offset:53248
	ds_read_b128 v[196:199], v141 offset:54272
	ds_read_b128 v[200:203], v141 offset:55296
	ds_read_b128 v[204:207], v141 offset:56320
	global_load_lds_dwordx4 v[174:175], off
	v_lshl_add_u64 v[174:175], v[228:229], 0, s[82:83]
	s_mov_b32 m0, s29
	s_nop 0
	global_load_lds_dwordx4 v[174:175], off
	s_barrier
; #define PG8_STAGE(bufoff, gbase, voff) do { _Pragma("unroll") for (int _i = 0; _i < 2; ++_i) \
;         __builtin_amdgcn_global_load_lds((const unsigned*)((const char*)(gbase) + (voff)[_i]), (LAS unsigned*)(lds + (bufoff) + ldsw + _i * 8192), 16, 0, 0); } while (0)
; #define PG8_MMA(ai, bj, At, Bt) do { __builtin_amdgcn_s_setprio(1); _Pragma("unroll") for (int m = 0; m < 4; ++m) _Pragma("unroll") for (int n = 0; n < 2; ++n) _Pragma("unroll") for (int k = 0; k < 2; ++k) \
;         acc[ai][bj][m][n] = __builtin_amdgcn_mfma_f32_16x16x32_bf16(Bt[n][k], At[m][k], acc[ai][bj][m][n], 0, 0, 0); __builtin_amdgcn_s_setprio(0); } while (0)
; #define PG8_WAIT_V(n) asm volatile("s_waitcnt vmcnt(" #n ")" ::: "memory")
; #define PG8_WAIT_L(n) asm volatile("s_waitcnt lgkmcnt(" #n ")" ::: "memory")
; #define PG8_BAR __builtin_amdgcn_s_barrier()
; #define PG8_SCHED __builtin_amdgcn_sched_barrier(0)
; template <class Epi, class Sched>
; __device__ __forceinline__ void gemm_phase(LAS unsigned char* lds, const Gemm g, const Sched& S, const Epi& E) {
;     ...
;             PG8_BAR; PG8_WAIT_L(0); PG8_MMA(1, 0, At, B0); PG8_BAR; PG8_SCHED;
;             PG8_STAGE(PG8_SB(1, 1), b3 + hstep, voffB);
;             PG8_WAIT_V(6); PG8_BAR; PG8_MMA(1, 1, At, B1); PG8_BAR;
	s_waitcnt lgkmcnt(0)
	s_setprio 1
	s_waitcnt lgkmcnt(0)
	v_mfma_f32_16x16x32_bf16 v[60:63], v[142:145], v[158:161], v[60:63]
	v_mfma_f32_16x16x32_bf16 v[56:59], v[150:153], v[158:161], v[56:59]
	v_mfma_f32_16x16x32_bf16 v[52:55], v[142:145], v[166:169], v[52:55]
	v_mfma_f32_16x16x32_bf16 v[48:51], v[150:153], v[166:169], v[48:51]
	v_mfma_f32_16x16x32_bf16 v[36:39], v[142:145], v[192:195], v[36:39]
	v_mfma_f32_16x16x32_bf16 v[32:35], v[150:153], v[192:195], v[32:35]
	v_mfma_f32_16x16x32_bf16 v[20:23], v[142:145], v[200:203], v[20:23]
	v_mfma_f32_16x16x32_bf16 v[16:19], v[150:153], v[200:203], v[16:19]
	v_mfma_f32_16x16x32_bf16 v[60:63], v[146:149], v[162:165], v[60:63]
	v_mfma_f32_16x16x32_bf16 v[56:59], v[154:157], v[162:165], v[56:59]
	v_mfma_f32_16x16x32_bf16 v[52:55], v[146:149], v[170:173], v[52:55]
	v_mfma_f32_16x16x32_bf16 v[48:51], v[154:157], v[170:173], v[48:51]
	v_mfma_f32_16x16x32_bf16 v[36:39], v[146:149], v[196:199], v[36:39]
	v_mfma_f32_16x16x32_bf16 v[32:35], v[154:157], v[196:199], v[32:35]
	v_mfma_f32_16x16x32_bf16 v[20:23], v[146:149], v[204:207], v[20:23]
	v_mfma_f32_16x16x32_bf16 v[16:19], v[154:157], v[204:207], v[16:19]
	s_setprio 0
	s_barrier
	s_add_u32 s18, s18, 0x80080
	s_addc_u32 s19, s19, 0
	s_add_i32 s20, s20, s23
	v_lshl_add_u64 v[142:143], s[18:19], 0, v[176:177]
	s_mov_b32 m0, s20
	s_nop 0
	global_load_lds_dwordx4 v[142:143], off
	v_lshl_add_u64 v[142:143], s[18:19], 0, v[128:129]
	s_add_i32 m0, s20, 0x2000
	s_nop 0
	global_load_lds_dwordx4 v[142:143], off
	s_waitcnt vmcnt(6)
	s_barrier
	s_setprio 1
	v_mfma_f32_16x16x32_bf16 v[44:47], v[208:211], v[158:161], v[44:47]
	v_mfma_f32_16x16x32_bf16 v[40:43], v[216:219], v[158:161], v[40:43]
	v_mfma_f32_16x16x32_bf16 v[28:31], v[208:211], v[166:169], v[28:31]
	v_mfma_f32_16x16x32_bf16 v[24:27], v[216:219], v[166:169], v[24:27]
	v_mfma_f32_16x16x32_bf16 v[12:15], v[208:211], v[192:195], v[12:15]
	v_mfma_f32_16x16x32_bf16 v[8:11], v[216:219], v[192:195], v[8:11]
	v_mfma_f32_16x16x32_bf16 v[4:7], v[208:211], v[200:203], v[4:7]
	v_mfma_f32_16x16x32_bf16 v[0:3], v[216:219], v[200:203], v[0:3]
	v_mfma_f32_16x16x32_bf16 v[44:47], v[212:215], v[162:165], v[44:47]
	v_mfma_f32_16x16x32_bf16 v[40:43], v[220:223], v[162:165], v[40:43]
	v_mfma_f32_16x16x32_bf16 v[28:31], v[212:215], v[170:173], v[28:31]
	v_mfma_f32_16x16x32_bf16 v[24:27], v[220:223], v[170:173], v[24:27]
	v_mfma_f32_16x16x32_bf16 v[12:15], v[212:215], v[196:199], v[12:15]
	v_mfma_f32_16x16x32_bf16 v[8:11], v[220:223], v[196:199], v[8:11]
	v_mfma_f32_16x16x32_bf16 v[4:7], v[212:215], v[204:207], v[4:7]
	v_mfma_f32_16x16x32_bf16 v[0:3], v[220:223], v[204:207], v[0:3]
	s_setprio 0
	s_add_i32 s38, s38, 2
	s_add_u32 s36, s36, 0x100
	s_addc_u32 s37, s37, 0
	s_add_u32 s16, s16, 0x100
	s_addc_u32 s17, s17, 0
	s_cmp_gt_u32 s38, 29
	s_barrier
	s_cbranch_scc0 .LBB0_852
; __device__ __forceinline__ unsigned cvt_pk_bf16(float lo, float hi) { return pk2(lo, hi); }
;     __device__ __forceinline__ void operator()(const f32x4 (&acc)[2][2][4][2], const Unit& u, int wr, int wc, int fr, int fq) const {
;         const int row0 = u.pm * BM + wr * 64 + fr, col0 = u.pn * BM + wc * 32 + 8 * fq;
; #pragma unroll
;         for (int ai = 0; ai < 2; ++ai)
; #pragma unroll
;             for (int m = 0; m < 4; ++m) { bf16_t* rowp = O + (size_t)(row0 + ai * HALF + m * 16) * ldc + col0;
; #pragma unroll
;                 for (int bj = 0; bj < 2; ++bj) { f32x4 v0 = acc[ai][bj][m][0], v1 = acc[ai][bj][m][1];
;                     if (ACT == 1) {
; #pragma unroll
;                         for (int j = 0; j < 4; ++j) { float a = fmaxf(v0[j], 0.f), b = fmaxf(v1[j], 0.f); v0[j] = a * a; v1[j] = b * b; } }
;                     u32x4 w; w.x = cvt_pk_bf16(v0[0], v0[1]); w.y = cvt_pk_bf16(v0[2], v0[3]); w.z = cvt_pk_bf16(v1[0], v1[1]); w.w = cvt_pk_bf16(v1[2], v1[3]);
;                     *(u32x4*)(rowp + bj * HALF) = w; } }
; template <class Epi, class Sched>
; __device__ __forceinline__ void gemm_phase(LAS unsigned char* lds, const Gemm g, const Sched& S, const Epi& E) {
;     ...
;         if constexpr (!Epi::AFTER_DRAIN) E(acc, cur, wr, wc, fr, fq);
;         if (!has_next) break;
; #pragma unroll
;         for (int a = 0; a < 2; ++a)
; #pragma unroll
;             for (int b = 0; b < 2; ++b)
; #pragma unroll
;                 for (int m = 0; m < 4; ++m)
; #pragma unroll
;                     for (int n = 0; n < 2; ++n) acc[a][b][m][n] = (f32x4){0.f, 0.f, 0.f, 0.f};
;         cur = nxt; cA = nA; cB = nB; ++ui;
	s_add_u32 s98, s12, 0x80080
	s_addc_u32 s99, s13, 0
	v_lshl_add_u64 v[174:175], s[98:99], 0, v[136:137]
	s_add_i32 m0, s7, 0xc000
	s_nop 0
	global_load_lds_dwordx4 v[174:175], off
	v_lshl_add_u64 v[174:175], s[98:99], 0, v[134:135]
	s_add_i32 m0, s7, 0xe000
	s_nop 0
	global_load_lds_dwordx4 v[174:175], off
	s_mov_b32 s100, 1
	v_lshl_add_u32 v148, s6, 8, v138
	v_lshl_or_b32 v142, s33, 8, v140
	v_ashrrev_i32_e32 v143, 31, v142
	v_mov_b64_e32 v[144:145], s[0:1]
	v_cvt_pk_bf16_f32 v68, v68, v69
	v_cvt_pk_bf16_f32 v69, v70, v71
	v_cvt_pk_bf16_f32 v70, v64, v65
	v_add_u32_e32 v64, 0x80, v148
	v_mad_i64_i32 v[146:147], s[16:17], v148, s78, v[144:145]
	v_lshlrev_b64 v[142:143], 1, v[142:143]
	v_cvt_pk_bf16_f32 v108, v108, v109
	v_cvt_pk_bf16_f32 v109, v110, v111
	v_cvt_pk_bf16_f32 v110, v104, v105
	v_or_b32_e32 v104, 16, v148
	v_mad_i64_i32 v[64:65], s[16:17], v64, s78, v[144:145]
	v_cvt_pk_bf16_f32 v44, v44, v45
	v_cvt_pk_bf16_f32 v45, v46, v47
	v_cvt_pk_bf16_f32 v46, v40, v41
	v_add_u32_e32 v40, 0x90, v148
	v_lshl_add_u64 v[146:147], v[146:147], 0, v[142:143]
	v_cvt_pk_bf16_f32 v111, v106, v107
	v_mad_i64_i32 v[104:105], s[16:17], v104, s78, v[144:145]
	v_cvt_pk_bf16_f32 v92, v92, v93
	v_cvt_pk_bf16_f32 v93, v94, v95
	v_cvt_pk_bf16_f32 v94, v88, v89
	v_or_b32_e32 v88, 32, v148
	v_lshl_add_u64 v[64:65], v[64:65], 0, v[142:143]
	v_cvt_pk_bf16_f32 v47, v42, v43
	v_mad_i64_i32 v[40:41], s[16:17], v40, s78, v[144:145]
	v_cvt_pk_bf16_f32 v28, v28, v29
	v_cvt_pk_bf16_f32 v29, v30, v31
	v_cvt_pk_bf16_f32 v30, v24, v25
	v_add_u32_e32 v24, 0xa0, v148
	global_store_dwordx4 v[146:147], v[108:111], off offset:256
	v_cvt_pk_bf16_f32 v95, v90, v91
	v_mad_i64_i32 v[88:89], s[16:17], v88, s78, v[144:145]
	v_lshl_add_u64 v[108:109], v[104:105], 0, v[142:143]
	v_cvt_pk_bf16_f32 v76, v76, v77
	v_cvt_pk_bf16_f32 v77, v78, v79
	v_cvt_pk_bf16_f32 v78, v72, v73
	v_or_b32_e32 v72, 48, v148
	global_store_dwordx4 v[64:65], v[44:47], off offset:256
	v_cvt_pk_bf16_f32 v31, v26, v27
	v_mad_i64_i32 v[24:25], s[16:17], v24, s78, v[144:145]
	v_lshl_add_u64 v[44:45], v[40:41], 0, v[142:143]
	v_cvt_pk_bf16_f32 v12, v12, v13
	v_cvt_pk_bf16_f32 v13, v14, v15
	v_cvt_pk_bf16_f32 v14, v8, v9
	v_add_u32_e32 v8, 0xb0, v148
	global_store_dwordx4 v[108:109], v[92:95], off offset:256
	v_cvt_pk_bf16_f32 v79, v74, v75
	v_mad_i64_i32 v[72:73], s[16:17], v72, s78, v[144:145]
	v_lshl_add_u64 v[92:93], v[88:89], 0, v[142:143]
	global_store_dwordx4 v[44:45], v[28:31], off offset:256
	v_cvt_pk_bf16_f32 v15, v10, v11
	v_mad_i64_i32 v[8:9], s[16:17], v8, s78, v[144:145]
	v_lshl_add_u64 v[28:29], v[24:25], 0, v[142:143]
	v_cvt_pk_bf16_f32 v124, v124, v125
	v_cvt_pk_bf16_f32 v125, v126, v127
	v_cvt_pk_bf16_f32 v126, v120, v121
	v_cvt_pk_bf16_f32 v127, v122, v123
	v_cvt_pk_bf16_f32 v104, v116, v117
	v_cvt_pk_bf16_f32 v105, v118, v119
	v_cvt_pk_bf16_f32 v106, v112, v113
	v_cvt_pk_bf16_f32 v107, v114, v115
	v_cvt_pk_bf16_f32 v88, v100, v101
	v_cvt_pk_bf16_f32 v89, v102, v103
	v_cvt_pk_bf16_f32 v90, v96, v97
	v_cvt_pk_bf16_f32 v91, v98, v99
	global_store_dwordx4 v[92:93], v[76:79], off offset:256
	v_cvt_pk_bf16_f32 v74, v80, v81
	v_cvt_pk_bf16_f32 v75, v82, v83
	v_lshl_add_u64 v[76:77], v[72:73], 0, v[142:143]
	v_cvt_pk_bf16_f32 v72, v84, v85
	v_cvt_pk_bf16_f32 v73, v86, v87
	v_cvt_pk_bf16_f32 v71, v66, v67
	v_cvt_pk_bf16_f32 v60, v60, v61
	v_cvt_pk_bf16_f32 v61, v62, v63
	v_cvt_pk_bf16_f32 v62, v56, v57
	v_cvt_pk_bf16_f32 v63, v58, v59
	v_cvt_pk_bf16_f32 v40, v52, v53
	v_cvt_pk_bf16_f32 v41, v54, v55
	v_cvt_pk_bf16_f32 v42, v48, v49
	v_cvt_pk_bf16_f32 v43, v50, v51
	v_cvt_pk_bf16_f32 v24, v36, v37
	v_cvt_pk_bf16_f32 v25, v38, v39
	v_cvt_pk_bf16_f32 v26, v32, v33
	v_cvt_pk_bf16_f32 v27, v34, v35
	global_store_dwordx4 v[28:29], v[12:15], off offset:256
	v_cvt_pk_bf16_f32 v10, v16, v17
	v_cvt_pk_bf16_f32 v11, v18, v19
	v_lshl_add_u64 v[12:13], v[8:9], 0, v[142:143]
	v_cvt_pk_bf16_f32 v8, v20, v21
	v_cvt_pk_bf16_f32 v9, v22, v23
	v_cvt_pk_bf16_f32 v4, v4, v5
	v_cvt_pk_bf16_f32 v5, v6, v7
	v_cvt_pk_bf16_f32 v6, v0, v1
	v_cvt_pk_bf16_f32 v7, v2, v3
	s_and_b64 vcc, exec, s[4:5]
	s_mov_b32 s33, s8
	s_mov_b32 s6, s10
	s_mov_b64 s[16:17], s[14:15]
	s_mov_b64 s[18:19], s[12:13]
	global_store_dwordx4 v[146:147], v[124:127], off
	global_store_dwordx4 v[108:109], v[104:107], off
	global_store_dwordx4 v[92:93], v[88:91], off
	global_store_dwordx4 v[76:77], v[72:75], off
	global_store_dwordx4 v[76:77], v[68:71], off offset:256
	global_store_dwordx4 v[64:65], v[60:63], off
	global_store_dwordx4 v[44:45], v[40:43], off
	global_store_dwordx4 v[28:29], v[24:27], off
	global_store_dwordx4 v[12:13], v[8:11], off
	global_store_dwordx4 v[12:13], v[4:7], off offset:256
	s_cbranch_vccz .LBB0_849
	s_mov_b32 s100, 0
	s_waitcnt vmcnt(0)
	s_cmpk_gt_u32 s2, 0xff
	s_mov_b32 s29, s45
	s_mov_b32 s30, s46
	s_mov_b32 s33, 0x10000
	s_cbranch_scc1 .LBB0_856
	s_barrier

; #define PG8_MMA(ai, bj, At, Bt) do { __builtin_amdgcn_s_setprio(1); _Pragma("unroll") for (int m = 0; m < 4; ++m) _Pragma("unroll") for (int n = 0; n < 2; ++n) _Pragma("unroll") for (int k = 0; k < 2; ++k) \
;         acc[ai][bj][m][n] = __builtin_amdgcn_mfma_f32_16x16x32_bf16(Bt[n][k], At[m][k], acc[ai][bj][m][n], 0, 0, 0); __builtin_amdgcn_s_setprio(0); } while (0)
; #define PG8_WAIT_V(n) asm volatile("s_waitcnt vmcnt(" #n ")" ::: "memory")
; #define PG8_BAR __builtin_amdgcn_s_barrier()
; template <class Epi, class Sched>
; __device__ __forceinline__ void gemm_phase(LAS unsigned char* lds, const Gemm g, const Sched& S, const Epi& E) {
;     ...
;             PG8_WAIT_V(6); PG8_BAR; PG8_MMA(1, 1, At, B1); PG8_BAR;
.Lgh_relax_win:
	s_waitcnt vmcnt(22)
	s_mov_b32 s100, 0
	s_branch .Lgh_back_win
